# attn: each wave issues 3 K/V DMAs in the QK gaps and 3 in the first PV gaps (less VMEM queue saturation)
# speedup vs baseline: 1.0113x; 1.0017x over previous
.Lattn_noskip:
	v_lshl_add_u32 v226, s36, 14, v233
	v_xor_b32_e32 v228, 32, v226
	v_xor_b32_e32 v229, 64, v226
	v_xor_b32_e32 v236, 0x60, v226
	ds_read_b128 v[82:85], v226
	ds_read_b128 v[86:89], v226 offset:4096
	ds_read_b128 v[90:93], v228
	ds_read_b128 v[94:97], v228 offset:4096
	ds_read_b128 v[98:101], v229
	ds_read_b128 v[102:105], v229 offset:4096
	ds_read_b128 v[106:109], v236
	ds_read_b128 v[110:113], v236 offset:4096
	ds_read_b128 v[114:117], v226 offset:8192
	ds_read_b128 v[118:121], v226 offset:12288
	ds_read_b128 v[122:125], v228 offset:8192
	ds_read_b128 v[126:129], v228 offset:12288
	ds_read_b128 v[130:133], v229 offset:8192
	ds_read_b128 v[134:137], v229 offset:12288
	ds_read_b128 v[138:141], v236 offset:8192
	s_cmp_ge_u32 s75, s72
	s_cbranch_scc1 .Lattn_qk_nodma
	s_mov_b32 s37, m0
	s_xor_b32 s6, s36, 1
	s_lshl_b32 s7, s6, 14
	s_add_i32 s7, s7, s69
	s_lshl_b32 s6, s6, 15
	s_add_i32 s6, s6, s70
	s_waitcnt lgkmcnt(14)
	v_mfma_f32_32x32x16_bf16 v[146:161], v[82:85], v[210:213], v[66:81]
	ds_read_b128 v[142:145], v236 offset:12288
	s_waitcnt lgkmcnt(14)
	v_mfma_f32_32x32x16_bf16 v[162:177], v[86:89], v[210:213], v[66:81]
	v_lshl_add_u64 v[82:83], v[238:239], 0, s[56:57]
	v_lshl_add_u64 v[84:85], v[240:241], 0, s[56:57]
	s_mov_b64 s[58:59], 0x40000
	v_lshl_add_u64 v[86:87], v[82:83], 0, s[58:59]
	s_mov_b32 m0, s7
	s_nop 0
	global_load_lds_dwordx4 v[86:87], off
	s_waitcnt lgkmcnt(13)
	v_mfma_f32_32x32x16_bf16 v[146:161], v[90:93], v[214:217], v[146:161]
	s_waitcnt lgkmcnt(12)
	v_mfma_f32_32x32x16_bf16 v[162:177], v[94:97], v[214:217], v[162:177]
	s_mov_b64 s[58:59], 0x20040000
	v_lshl_add_u64 v[86:87], v[84:85], 0, s[58:59]
	s_mov_b32 m0, s6
	s_nop 0
	global_load_lds_dwordx4 v[86:87], off
	s_waitcnt lgkmcnt(11)
	v_mfma_f32_32x32x16_bf16 v[146:161], v[98:101], v[218:221], v[146:161]
	s_waitcnt lgkmcnt(10)
	v_mfma_f32_32x32x16_bf16 v[162:177], v[102:105], v[218:221], v[162:177]
	s_mov_b64 s[58:59], 0x20040080
	v_lshl_add_u64 v[86:87], v[84:85], 0, s[58:59]
	s_add_i32 m0, s6, 0x2000
	s_nop 0
	global_load_lds_dwordx4 v[86:87], off
	s_waitcnt lgkmcnt(9)
	v_mfma_f32_32x32x16_bf16 v[146:161], v[106:109], v[222:225], v[146:161]
	s_waitcnt lgkmcnt(8)
	v_mfma_f32_32x32x16_bf16 v[162:177], v[110:113], v[222:225], v[162:177]
	s_waitcnt lgkmcnt(7)
	v_mfma_f32_32x32x16_bf16 v[178:193], v[114:117], v[210:213], v[66:81]
	s_waitcnt lgkmcnt(6)
	v_mfma_f32_32x32x16_bf16 v[194:209], v[118:121], v[210:213], v[66:81]
	s_waitcnt lgkmcnt(5)
	v_mfma_f32_32x32x16_bf16 v[178:193], v[122:125], v[214:217], v[178:193]
	s_waitcnt lgkmcnt(4)
	v_mfma_f32_32x32x16_bf16 v[194:209], v[126:129], v[214:217], v[194:209]
	s_waitcnt lgkmcnt(3)
	v_mfma_f32_32x32x16_bf16 v[178:193], v[130:133], v[218:221], v[178:193]
	s_waitcnt lgkmcnt(2)
	v_mfma_f32_32x32x16_bf16 v[194:209], v[134:137], v[218:221], v[194:209]
	s_waitcnt lgkmcnt(1)
	v_mfma_f32_32x32x16_bf16 v[178:193], v[138:141], v[222:225], v[178:193]
	s_waitcnt lgkmcnt(0)
	v_mfma_f32_32x32x16_bf16 v[194:209], v[142:145], v[222:225], v[194:209]
	s_mov_b32 m0, s37
	s_branch .Lattn_qk_done

.LBB0_679:
	s_cmp_ge_u32 s75, s72
	s_cbranch_scc1 .Lattn_pv_nodma
	v_lshl_add_u32 v227, s36, 15, v230
	s_mov_b32 s37, m0
	s_xor_b32 s6, s36, 1
	s_lshl_b32 s7, s6, 14
	s_add_i32 s7, s7, s69
	s_lshl_b32 s6, s6, 15
	s_add_i32 s6, s6, s70
	ds_read_b64_tr_b16 v[114:115], v227 offset:32768
	ds_read_b64_tr_b16 v[116:117], v227 offset:33280
	ds_read_b64_tr_b16 v[118:119], v227 offset:33792
	ds_read_b64_tr_b16 v[120:121], v227 offset:34304
	ds_read_b64_tr_b16 v[122:123], v227 offset:34816
	ds_read_b64_tr_b16 v[124:125], v227 offset:35328
	ds_read_b64_tr_b16 v[126:127], v227 offset:35840
	ds_read_b64_tr_b16 v[128:129], v227 offset:36352
	ds_read_b64_tr_b16 v[130:131], v227 offset:36864
	ds_read_b64_tr_b16 v[132:133], v227 offset:37376
	ds_read_b64_tr_b16 v[134:135], v227 offset:37888
	ds_read_b64_tr_b16 v[136:137], v227 offset:38400
	v_exp_f32_e32 v146, v146
	v_exp_f32_e32 v147, v147
	v_exp_f32_e32 v162, v162
	v_exp_f32_e32 v163, v163
	v_exp_f32_e32 v148, v148
	v_exp_f32_e32 v149, v149
	v_exp_f32_e32 v164, v164
	v_exp_f32_e32 v165, v165
	v_cvt_pk_bf16_f32 v82, v146, v147
	v_cvt_pk_bf16_f32 v90, v162, v163
	v_exp_f32_e32 v150, v150
	v_exp_f32_e32 v151, v151
	v_exp_f32_e32 v166, v166
	v_exp_f32_e32 v167, v167
	v_cvt_pk_bf16_f32 v83, v148, v149
	v_cvt_pk_bf16_f32 v91, v164, v165
	v_exp_f32_e32 v152, v152
	v_exp_f32_e32 v153, v153
	v_exp_f32_e32 v168, v168
	v_exp_f32_e32 v169, v169
	v_cvt_pk_bf16_f32 v84, v150, v151
	v_cvt_pk_bf16_f32 v92, v166, v167
	v_exp_f32_e32 v154, v154
	v_exp_f32_e32 v155, v155
	v_exp_f32_e32 v170, v170
	v_exp_f32_e32 v171, v171
	v_cvt_pk_bf16_f32 v85, v152, v153
	v_cvt_pk_bf16_f32 v93, v168, v169
	v_exp_f32_e32 v156, v156
	v_exp_f32_e32 v157, v157
	v_exp_f32_e32 v172, v172
	v_exp_f32_e32 v173, v173
	v_cvt_pk_bf16_f32 v86, v154, v155
	v_cvt_pk_bf16_f32 v94, v170, v171
	v_exp_f32_e32 v158, v158
	v_exp_f32_e32 v159, v159
	v_exp_f32_e32 v174, v174
	v_exp_f32_e32 v175, v175
	v_cvt_pk_bf16_f32 v87, v156, v157
	v_cvt_pk_bf16_f32 v95, v172, v173
	v_exp_f32_e32 v160, v160
	v_exp_f32_e32 v161, v161
	v_exp_f32_e32 v176, v176
	v_exp_f32_e32 v177, v177
	v_cvt_pk_bf16_f32 v88, v158, v159
	v_cvt_pk_bf16_f32 v96, v174, v175
	s_nop 0
	v_cvt_pk_bf16_f32 v89, v160, v161
	v_cvt_pk_bf16_f32 v97, v176, v177
	s_waitcnt lgkmcnt(10)
	v_mfma_f32_32x32x16_bf16 v[50:65], v[82:85], v[114:117], v[50:65]
	ds_read_b64_tr_b16 v[138:139], v227 offset:38912
	ds_read_b64_tr_b16 v[140:141], v227 offset:39424
	v_exp_f32_e32 v178, v178
	v_exp_f32_e32 v179, v179
	s_waitcnt lgkmcnt(10)
	v_mfma_f32_32x32x16_bf16 v[50:65], v[86:89], v[118:121], v[50:65]
	ds_read_b64_tr_b16 v[142:143], v227 offset:39936
	ds_read_b64_tr_b16 v[144:145], v227 offset:40448
	s_add_u32 s58, s56, 0x60000
	s_addc_u32 s59, s57, 0
	v_lshl_add_u64 v[228:229], v[238:239], 0, s[58:59]
	s_add_i32 m0, s7, 0x2000
	s_nop 0
	global_load_lds_dwordx4 v[228:229], off
	v_exp_f32_e32 v180, v180
	v_exp_f32_e32 v181, v181
	v_cvt_pk_bf16_f32 v98, v178, v179
	s_waitcnt lgkmcnt(10)
	v_mfma_f32_32x32x16_bf16 v[50:65], v[90:93], v[122:125], v[50:65]
	ds_read_b64_tr_b16 v[114:115], v227 offset:40960
	ds_read_b64_tr_b16 v[116:117], v227 offset:41472
	v_exp_f32_e32 v182, v182
	v_exp_f32_e32 v183, v183
	v_cvt_pk_bf16_f32 v99, v180, v181
	s_waitcnt lgkmcnt(10)
	v_mfma_f32_32x32x16_bf16 v[50:65], v[94:97], v[126:129], v[50:65]
	ds_read_b64_tr_b16 v[118:119], v227 offset:41984
	ds_read_b64_tr_b16 v[120:121], v227 offset:42496
	s_add_u32 s58, s56, 0x20060000
	s_addc_u32 s59, s57, 0
	v_lshl_add_u64 v[228:229], v[240:241], 0, s[58:59]
	s_add_i32 m0, s6, 0x4000
	s_nop 0
	global_load_lds_dwordx4 v[228:229], off
	v_exp_f32_e32 v184, v184
	v_exp_f32_e32 v185, v185
	v_cvt_pk_bf16_f32 v100, v182, v183
	s_waitcnt lgkmcnt(10)
	v_mfma_f32_32x32x16_bf16 v[34:49], v[82:85], v[130:133], v[34:49]
	ds_read_b64_tr_b16 v[122:123], v227 offset:43008
	ds_read_b64_tr_b16 v[124:125], v227 offset:43520
	v_exp_f32_e32 v186, v186
	v_exp_f32_e32 v187, v187
	v_cvt_pk_bf16_f32 v101, v184, v185
	s_waitcnt lgkmcnt(10)
	v_mfma_f32_32x32x16_bf16 v[34:49], v[86:89], v[134:137], v[34:49]
	ds_read_b64_tr_b16 v[126:127], v227 offset:44032
	ds_read_b64_tr_b16 v[128:129], v227 offset:44544
	s_add_u32 s58, s56, 0x20060080
	s_addc_u32 s59, s57, 0
	v_lshl_add_u64 v[228:229], v[240:241], 0, s[58:59]
	s_add_i32 m0, s6, 0x6000
	s_nop 0
	global_load_lds_dwordx4 v[228:229], off
	v_exp_f32_e32 v188, v188
	v_exp_f32_e32 v189, v189
	v_cvt_pk_bf16_f32 v102, v186, v187
	s_waitcnt lgkmcnt(10)
	v_mfma_f32_32x32x16_bf16 v[34:49], v[90:93], v[138:141], v[34:49]
	ds_read_b64_tr_b16 v[130:131], v227 offset:45056
	ds_read_b64_tr_b16 v[132:133], v227 offset:45568
	s_mov_b32 m0, s37
	v_exp_f32_e32 v190, v190
	v_exp_f32_e32 v191, v191
	v_cvt_pk_bf16_f32 v103, v188, v189
	s_waitcnt lgkmcnt(10)
	v_mfma_f32_32x32x16_bf16 v[34:49], v[94:97], v[142:145], v[34:49]
	ds_read_b64_tr_b16 v[134:135], v227 offset:46080
	ds_read_b64_tr_b16 v[136:137], v227 offset:46592
	v_exp_f32_e32 v192, v192
	v_exp_f32_e32 v193, v193
	v_cvt_pk_bf16_f32 v104, v190, v191
	s_waitcnt lgkmcnt(10)
	v_mfma_f32_32x32x16_bf16 v[18:33], v[82:85], v[114:117], v[18:33]
	ds_read_b64_tr_b16 v[138:139], v227 offset:47104
	ds_read_b64_tr_b16 v[140:141], v227 offset:47616
	v_exp_f32_e32 v194, v194
	v_exp_f32_e32 v195, v195
	v_cvt_pk_bf16_f32 v105, v192, v193
	s_waitcnt lgkmcnt(10)
	v_mfma_f32_32x32x16_bf16 v[18:33], v[86:89], v[118:121], v[18:33]
	ds_read_b64_tr_b16 v[142:143], v227 offset:48128
	ds_read_b64_tr_b16 v[144:145], v227 offset:48640
	v_exp_f32_e32 v196, v196
	v_exp_f32_e32 v197, v197
	v_cvt_pk_bf16_f32 v106, v194, v195
	s_waitcnt lgkmcnt(10)
	v_mfma_f32_32x32x16_bf16 v[18:33], v[90:93], v[122:125], v[18:33]
	ds_read_b64_tr_b16 v[114:115], v227 offset:49152
	ds_read_b64_tr_b16 v[116:117], v227 offset:49664
	v_exp_f32_e32 v198, v198
	v_exp_f32_e32 v199, v199
	v_cvt_pk_bf16_f32 v107, v196, v197
	s_waitcnt lgkmcnt(10)
	v_mfma_f32_32x32x16_bf16 v[18:33], v[94:97], v[126:129], v[18:33]
	ds_read_b64_tr_b16 v[118:119], v227 offset:50176
	ds_read_b64_tr_b16 v[120:121], v227 offset:50688
	v_exp_f32_e32 v200, v200
	v_exp_f32_e32 v201, v201
	v_cvt_pk_bf16_f32 v108, v198, v199
	s_waitcnt lgkmcnt(10)
	v_mfma_f32_32x32x16_bf16 v[2:17], v[82:85], v[130:133], v[2:17]
	ds_read_b64_tr_b16 v[122:123], v227 offset:51200
	ds_read_b64_tr_b16 v[124:125], v227 offset:51712
	v_exp_f32_e32 v202, v202
	v_exp_f32_e32 v203, v203
	v_cvt_pk_bf16_f32 v109, v200, v201
	s_waitcnt lgkmcnt(10)
	v_mfma_f32_32x32x16_bf16 v[2:17], v[86:89], v[134:137], v[2:17]
	ds_read_b64_tr_b16 v[126:127], v227 offset:52224
	ds_read_b64_tr_b16 v[128:129], v227 offset:52736
	v_exp_f32_e32 v204, v204
	v_exp_f32_e32 v205, v205
	v_cvt_pk_bf16_f32 v110, v202, v203
	s_waitcnt lgkmcnt(10)
	v_mfma_f32_32x32x16_bf16 v[2:17], v[90:93], v[138:141], v[2:17]
	ds_read_b64_tr_b16 v[130:131], v227 offset:53248
	ds_read_b64_tr_b16 v[132:133], v227 offset:53760
	v_exp_f32_e32 v206, v206
	v_exp_f32_e32 v207, v207
	v_cvt_pk_bf16_f32 v111, v204, v205
	s_waitcnt lgkmcnt(10)
	v_mfma_f32_32x32x16_bf16 v[2:17], v[94:97], v[142:145], v[2:17]
	ds_read_b64_tr_b16 v[134:135], v227 offset:54272
	ds_read_b64_tr_b16 v[136:137], v227 offset:54784
	v_exp_f32_e32 v208, v208
	v_exp_f32_e32 v209, v209
	v_cvt_pk_bf16_f32 v112, v206, v207
	s_waitcnt lgkmcnt(10)
	v_mfma_f32_32x32x16_bf16 v[50:65], v[98:101], v[114:117], v[50:65]
	ds_read_b64_tr_b16 v[138:139], v227 offset:55296
	ds_read_b64_tr_b16 v[140:141], v227 offset:55808
	v_cvt_pk_bf16_f32 v113, v208, v209
	v_add_f32_e32 v226, v162, v146
	v_add_f32_e32 v0, v194, v178
	s_waitcnt lgkmcnt(10)
	v_mfma_f32_32x32x16_bf16 v[50:65], v[102:105], v[118:121], v[50:65]
	ds_read_b64_tr_b16 v[142:143], v227 offset:56320
	ds_read_b64_tr_b16 v[144:145], v227 offset:56832
	v_add_f32_e32 v228, v163, v147
	v_add_f32_e32 v229, v195, v179
	v_add_f32_e32 v226, v228, v226
	v_add_f32_e32 v0, v229, v0
	s_waitcnt lgkmcnt(10)
	v_mfma_f32_32x32x16_bf16 v[50:65], v[106:109], v[122:125], v[50:65]
	ds_read_b64_tr_b16 v[114:115], v227 offset:57344
	ds_read_b64_tr_b16 v[116:117], v227 offset:57856
	v_add_f32_e32 v228, v164, v148
	v_add_f32_e32 v229, v196, v180
	v_add_f32_e32 v226, v228, v226
	v_add_f32_e32 v0, v229, v0
	s_waitcnt lgkmcnt(10)
	v_mfma_f32_32x32x16_bf16 v[50:65], v[110:113], v[126:129], v[50:65]
	ds_read_b64_tr_b16 v[118:119], v227 offset:58368
	ds_read_b64_tr_b16 v[120:121], v227 offset:58880
	v_add_f32_e32 v228, v165, v149
	v_add_f32_e32 v229, v197, v181
	v_add_f32_e32 v226, v228, v226
	v_add_f32_e32 v0, v229, v0
	s_waitcnt lgkmcnt(10)
	v_mfma_f32_32x32x16_bf16 v[34:49], v[98:101], v[130:133], v[34:49]
	ds_read_b64_tr_b16 v[122:123], v227 offset:59392
	ds_read_b64_tr_b16 v[124:125], v227 offset:59904
	v_add_f32_e32 v228, v166, v150
	v_add_f32_e32 v229, v198, v182
	v_add_f32_e32 v226, v228, v226
	v_add_f32_e32 v0, v229, v0
	s_waitcnt lgkmcnt(10)
	v_mfma_f32_32x32x16_bf16 v[34:49], v[102:105], v[134:137], v[34:49]
	ds_read_b64_tr_b16 v[126:127], v227 offset:60416
	ds_read_b64_tr_b16 v[128:129], v227 offset:60928
	v_add_f32_e32 v228, v167, v151
	v_add_f32_e32 v229, v199, v183
	v_add_f32_e32 v226, v228, v226
	v_add_f32_e32 v0, v229, v0
	s_waitcnt lgkmcnt(10)
	v_mfma_f32_32x32x16_bf16 v[34:49], v[106:109], v[138:141], v[34:49]
	ds_read_b64_tr_b16 v[130:131], v227 offset:61440
	ds_read_b64_tr_b16 v[132:133], v227 offset:61952
	v_add_f32_e32 v228, v168, v152
	v_add_f32_e32 v229, v200, v184
	v_add_f32_e32 v226, v228, v226
	v_add_f32_e32 v0, v229, v0
	s_waitcnt lgkmcnt(10)
	v_mfma_f32_32x32x16_bf16 v[34:49], v[110:113], v[142:145], v[34:49]
	ds_read_b64_tr_b16 v[134:135], v227 offset:62464
	ds_read_b64_tr_b16 v[136:137], v227 offset:62976
	v_add_f32_e32 v228, v169, v153
	v_add_f32_e32 v229, v201, v185
	v_add_f32_e32 v226, v228, v226
	v_add_f32_e32 v0, v229, v0
	s_waitcnt lgkmcnt(10)
	v_mfma_f32_32x32x16_bf16 v[18:33], v[98:101], v[114:117], v[18:33]
	ds_read_b64_tr_b16 v[138:139], v227 offset:63488
	ds_read_b64_tr_b16 v[140:141], v227 offset:64000
	v_add_f32_e32 v228, v170, v154
	v_add_f32_e32 v229, v202, v186
	v_add_f32_e32 v226, v228, v226
	v_add_f32_e32 v0, v229, v0
	s_waitcnt lgkmcnt(10)
	v_mfma_f32_32x32x16_bf16 v[18:33], v[102:105], v[118:121], v[18:33]
	ds_read_b64_tr_b16 v[142:143], v227 offset:64512
	ds_read_b64_tr_b16 v[144:145], v227 offset:65024
	v_add_f32_e32 v228, v171, v155
	v_add_f32_e32 v229, v203, v187
	v_add_f32_e32 v226, v228, v226
	v_add_f32_e32 v0, v229, v0
	s_waitcnt lgkmcnt(10)
	v_mfma_f32_32x32x16_bf16 v[18:33], v[106:109], v[122:125], v[18:33]
	v_add_f32_e32 v228, v172, v156
	v_add_f32_e32 v229, v204, v188
	v_add_f32_e32 v226, v228, v226
	v_add_f32_e32 v0, v229, v0
	s_waitcnt lgkmcnt(8)
	v_mfma_f32_32x32x16_bf16 v[18:33], v[110:113], v[126:129], v[18:33]
	v_add_f32_e32 v228, v173, v157
	v_add_f32_e32 v229, v205, v189
	v_add_f32_e32 v226, v228, v226
	v_add_f32_e32 v0, v229, v0
	s_waitcnt lgkmcnt(6)
	v_mfma_f32_32x32x16_bf16 v[2:17], v[98:101], v[130:133], v[2:17]
	v_add_f32_e32 v228, v174, v158
	v_add_f32_e32 v229, v206, v190
	v_add_f32_e32 v226, v228, v226
	v_add_f32_e32 v0, v229, v0
	s_waitcnt lgkmcnt(4)
	v_mfma_f32_32x32x16_bf16 v[2:17], v[102:105], v[134:137], v[2:17]
	v_add_f32_e32 v228, v175, v159
	v_add_f32_e32 v229, v207, v191
	v_add_f32_e32 v226, v228, v226
	v_add_f32_e32 v0, v229, v0
	s_waitcnt lgkmcnt(2)
	v_mfma_f32_32x32x16_bf16 v[2:17], v[106:109], v[138:141], v[2:17]
	v_add_f32_e32 v228, v176, v160
	v_add_f32_e32 v229, v208, v192
	v_add_f32_e32 v226, v228, v226
	v_add_f32_e32 v0, v229, v0
	s_waitcnt lgkmcnt(0)
	v_mfma_f32_32x32x16_bf16 v[2:17], v[110:113], v[142:145], v[2:17]
	v_add_f32_e32 v228, v177, v161
	v_add_f32_e32 v229, v209, v193
	v_add_f32_e32 v226, v228, v226
	v_add_f32_e32 v0, v229, v0
	v_add_f32_e32 v226, v226, v0
	v_add_f32_e32 v0, v237, v226
	s_branch .Lattn_pv_done

.Lattn_pv_done:
	s_addk_i32 s68, 0x80
	s_add_u32 s56, s56, 0x40000
	s_addc_u32 s57, s57, 0
	s_cmp_eq_u32 s74, s56
	s_cbranch_scc1 .LBB0_682
	v_mov_b32_e32 v235, v236
	s_mov_b32 s24, s75
	s_branch .LBB0_666
